# quarter-loop MFMA phase rebalancing: 16 MFMAs per half spread 6/5/3/2 over the four barrier phases (2 moved into the LDS-DMA issue phase)
# speedup vs baseline: 1.0032x; 1.0004x over previous
.Lq5_top:
	ds_read_b128 v[148:151], v214
	ds_read_b128 v[152:155], v214 offset:1024
	ds_read_b128 v[156:159], v214 offset:2048
	ds_read_b128 v[160:163], v214 offset:3072
	v_lshl_add_u64 v[2:3], s[34:35], 0, v[200:201]
	s_add_i32 m0, s48, 0xc000
	ds_read_b128 v[188:191], v216
	ds_read_b128 v[192:195], v216 offset:1024
	ds_read_b128 v[180:183], v216 offset:2048
	ds_read_b128 v[184:187], v216 offset:3072
	ds_read_b128 v[172:175], v216 offset:4096
	ds_read_b128 v[176:179], v216 offset:5120
	ds_read_b128 v[164:167], v216 offset:6144
	ds_read_b128 v[168:171], v216 offset:7168
	v_lshl_add_u64 v[2:3], s[34:35], 0, v[202:203]
	s_add_i32 m0, s48, 0xe000
	s_nop 0
	s_setprio 1
	v_mfma_f32_16x16x32_bf16 v[128:131], v[4:7], v[44:47], v[128:131]
	v_mfma_f32_16x16x32_bf16 v[124:127], v[12:15], v[44:47], v[124:127]
	v_mfma_f32_16x16x32_bf16 v[120:123], v[4:7], v[36:39], v[120:123]
	v_mfma_f32_16x16x32_bf16 v[116:119], v[12:15], v[36:39], v[116:119]
	v_mfma_f32_16x16x32_bf16 v[104:107], v[4:7], v[28:31], v[104:107]
	v_mfma_f32_16x16x32_bf16 v[100:103], v[12:15], v[28:31], v[100:103]
	s_setprio 0
	s_barrier
	v_cmp_ne_u32_e64 s[2:3], 1, v217
	s_andn2_b64 vcc, exec, s[26:27]
	s_add_u32 s56, s34, 0xfff80080
	s_addc_u32 s57, s35, -1
	s_cmp_eq_u32 s77, 10
	s_cselect_b32 s59, s39, s57
	s_cselect_b32 s58, s38, s56
	s_cselect_b32 s57, s47, s41
	s_cselect_b32 s56, s46, s18
	s_setprio 1
	v_mfma_f32_16x16x32_bf16 v[88:91], v[4:7], v[20:23], v[88:91]
	v_mfma_f32_16x16x32_bf16 v[84:87], v[12:15], v[20:23], v[84:87]
	v_mfma_f32_16x16x32_bf16 v[128:131], v[8:11], v[48:51], v[128:131]
	v_mfma_f32_16x16x32_bf16 v[124:127], v[16:19], v[48:51], v[124:127]
	v_mfma_f32_16x16x32_bf16 v[120:123], v[8:11], v[40:43], v[120:123]
	s_setprio 0
	s_waitcnt lgkmcnt(0)
	s_barrier
	s_setprio 1
	v_mfma_f32_16x16x32_bf16 v[116:119], v[16:19], v[40:43], v[116:119]
	v_mfma_f32_16x16x32_bf16 v[104:107], v[8:11], v[32:35], v[104:107]
	v_mfma_f32_16x16x32_bf16 v[100:103], v[16:19], v[32:35], v[100:103]
	s_setprio 0
	s_waitcnt vmcnt(8)
	s_barrier
	s_setprio 1
	v_mfma_f32_16x16x32_bf16 v[88:91], v[8:11], v[24:27], v[88:91]
	v_mfma_f32_16x16x32_bf16 v[84:87], v[16:19], v[24:27], v[84:87]
	s_setprio 0
	s_mov_b32 m0, s49
	v_lshl_add_u64 v[2:3], s[56:57], 0, v[198:199]
	s_add_u32 s78, s56, 0x80000
	global_load_lds_dwordx4 v[2:3], off
	v_lshl_add_u64 v[204:205], s[56:57], 0, v[196:197]
	s_mov_b32 m0, s50
	s_addc_u32 s79, s57, 0
	global_load_lds_dwordx4 v[204:205], off
	v_lshl_add_u64 v[206:207], s[78:79], 0, v[198:199]
	s_mov_b32 m0, s51
	v_lshl_add_u64 v[208:209], s[58:59], 0, v[196:197]
	v_lshl_add_u64 v[206:207], s[78:79], 0, v[196:197]
	s_mov_b32 m0, s60
	s_and_b64 vcc, exec, s[2:3]
	v_lshl_add_u64 v[206:207], s[58:59], 0, v[198:199]
	s_mov_b32 m0, s48
	s_nop 0
	global_load_lds_dwordx4 v[206:207], off
	s_mov_b32 m0, s61
	s_nop 0
	global_load_lds_dwordx4 v[208:209], off
	s_barrier
	v_add_u32_e32 v1, 0x18000, v213
	ds_read_b128 v[4:7], v1
	ds_read_b128 v[8:11], v1 offset:1024
	ds_read_b128 v[12:15], v1 offset:2048
	ds_read_b128 v[16:19], v1 offset:3072
	v_add_u32_e32 v1, 0x1c000, v213
	s_add_u32 s58, s58, 0x80000
	s_addc_u32 s59, s59, 0
	s_mov_b32 m0, s62
	v_lshl_add_u64 v[218:219], s[58:59], 0, v[198:199]
	ds_read_b128 v[44:47], v216 offset:32768
	ds_read_b128 v[48:51], v216 offset:33792
	ds_read_b128 v[36:39], v216 offset:34816
	ds_read_b128 v[40:43], v216 offset:35840
	ds_read_b128 v[28:31], v216 offset:36864
	ds_read_b128 v[32:35], v216 offset:37888
	ds_read_b128 v[20:23], v216 offset:38912
	ds_read_b128 v[24:27], v216 offset:39936
	v_lshl_add_u64 v[218:219], s[58:59], 0, v[196:197]
	s_mov_b32 m0, s63
	s_nop 0
	s_setprio 1
	v_mfma_f32_16x16x32_bf16 v[128:131], v[148:151], v[188:191], v[128:131]
	v_mfma_f32_16x16x32_bf16 v[124:127], v[156:159], v[188:191], v[124:127]
	v_mfma_f32_16x16x32_bf16 v[120:123], v[148:151], v[180:183], v[120:123]
	v_mfma_f32_16x16x32_bf16 v[116:119], v[156:159], v[180:183], v[116:119]
	v_mfma_f32_16x16x32_bf16 v[104:107], v[148:151], v[172:175], v[104:107]
	v_mfma_f32_16x16x32_bf16 v[100:103], v[156:159], v[172:175], v[100:103]
	s_setprio 0
	s_barrier
	s_and_b64 vcc, exec, s[2:3]
	s_setprio 1
	v_mfma_f32_16x16x32_bf16 v[88:91], v[148:151], v[164:167], v[88:91]
	v_mfma_f32_16x16x32_bf16 v[84:87], v[156:159], v[164:167], v[84:87]
	v_mfma_f32_16x16x32_bf16 v[128:131], v[152:155], v[192:195], v[128:131]
	v_mfma_f32_16x16x32_bf16 v[124:127], v[160:163], v[192:195], v[124:127]
	v_mfma_f32_16x16x32_bf16 v[120:123], v[152:155], v[184:187], v[120:123]
	s_setprio 0
	s_waitcnt lgkmcnt(0)
	s_barrier
	s_setprio 1
	v_mfma_f32_16x16x32_bf16 v[116:119], v[160:163], v[184:187], v[116:119]
	v_mfma_f32_16x16x32_bf16 v[104:107], v[152:155], v[176:179], v[104:107]
	v_mfma_f32_16x16x32_bf16 v[100:103], v[160:163], v[176:179], v[100:103]
	s_setprio 0
	s_waitcnt vmcnt(8)
	s_barrier
	s_setprio 1
	v_mfma_f32_16x16x32_bf16 v[88:91], v[152:155], v[168:171], v[88:91]
	v_mfma_f32_16x16x32_bf16 v[84:87], v[160:163], v[168:171], v[84:87]
	s_setprio 0
	s_mov_b32 m0, s66
	v_lshl_add_u64 v[2:3], v[2:3], 0, s[16:17]
	s_add_u32 s56, s56, 0x80080
	global_load_lds_dwordx4 v[2:3], off
	v_lshl_add_u64 v[2:3], v[204:205], 0, s[16:17]
	s_mov_b32 m0, s67
	s_addc_u32 s57, s57, 0
	global_load_lds_dwordx4 v[2:3], off
	v_lshl_add_u64 v[2:3], s[56:57], 0, v[198:199]
	s_mov_b32 m0, s70
	s_and_b64 vcc, exec, s[2:3]
	v_lshl_add_u64 v[2:3], s[56:57], 0, v[196:197]
	s_mov_b32 m0, s71
	s_nop 0
	v_lshl_add_u64 v[2:3], v[206:207], 0, s[16:17]
	s_mov_b32 m0, s68
	s_nop 0
	global_load_lds_dwordx4 v[2:3], off
	v_lshl_add_u64 v[2:3], v[208:209], 0, s[16:17]
	s_mov_b32 m0, s69
	s_nop 0
	global_load_lds_dwordx4 v[2:3], off
	s_barrier
	s_add_i32 s77, s77, 2
	s_add_u32 s34, s34, 0x100
	s_addc_u32 s35, s35, 0
	s_add_u32 s18, s18, 0x100
	s_addc_u32 s41, s41, 0
	s_cmp_gt_u32 s77, 13
	ds_read_b128 v[148:151], v215
	ds_read_b128 v[152:155], v215 offset:1024
	ds_read_b128 v[156:159], v215 offset:2048
	ds_read_b128 v[160:163], v215 offset:3072
	v_lshl_add_u64 v[2:3], s[34:35], 0, v[200:201]
	s_add_i32 m0, s48, 0xc000
	ds_read_b128 v[188:191], v216 offset:16384
	ds_read_b128 v[192:195], v216 offset:17408
	ds_read_b128 v[180:183], v216 offset:18432
	ds_read_b128 v[184:187], v216 offset:19456
	ds_read_b128 v[172:175], v216 offset:20480
	ds_read_b128 v[176:179], v216 offset:21504
	ds_read_b128 v[164:167], v216 offset:22528
	ds_read_b128 v[168:171], v216 offset:23552
	v_lshl_add_u64 v[2:3], s[34:35], 0, v[202:203]
	s_add_i32 m0, s48, 0xe000
	s_nop 0
	s_setprio 1
	v_mfma_f32_16x16x32_bf16 v[128:131], v[4:7], v[44:47], v[128:131]
	v_mfma_f32_16x16x32_bf16 v[124:127], v[12:15], v[44:47], v[124:127]
	v_mfma_f32_16x16x32_bf16 v[120:123], v[4:7], v[36:39], v[120:123]
	v_mfma_f32_16x16x32_bf16 v[116:119], v[12:15], v[36:39], v[116:119]
	v_mfma_f32_16x16x32_bf16 v[104:107], v[4:7], v[28:31], v[104:107]
	v_mfma_f32_16x16x32_bf16 v[100:103], v[12:15], v[28:31], v[100:103]
	s_setprio 0
	s_barrier
	v_cmp_ne_u32_e64 s[2:3], 1, v217
	s_andn2_b64 vcc, exec, s[26:27]
	s_add_u32 s56, s34, 0xfff80080
	s_addc_u32 s57, s35, -1
	s_cmp_eq_u32 s77, 12
	s_cselect_b32 s59, s39, s57
	s_cselect_b32 s58, s38, s56
	s_cselect_b32 s57, s47, s41
	s_cselect_b32 s56, s46, s18
	s_setprio 1
	v_mfma_f32_16x16x32_bf16 v[88:91], v[4:7], v[20:23], v[88:91]
	v_mfma_f32_16x16x32_bf16 v[84:87], v[12:15], v[20:23], v[84:87]
	v_mfma_f32_16x16x32_bf16 v[128:131], v[8:11], v[48:51], v[128:131]
	v_mfma_f32_16x16x32_bf16 v[124:127], v[16:19], v[48:51], v[124:127]
	v_mfma_f32_16x16x32_bf16 v[120:123], v[8:11], v[40:43], v[120:123]
	s_setprio 0
	s_waitcnt lgkmcnt(0)
	s_barrier
	s_setprio 1
	v_mfma_f32_16x16x32_bf16 v[116:119], v[16:19], v[40:43], v[116:119]
	v_mfma_f32_16x16x32_bf16 v[104:107], v[8:11], v[32:35], v[104:107]
	v_mfma_f32_16x16x32_bf16 v[100:103], v[16:19], v[32:35], v[100:103]
	s_setprio 0
	s_waitcnt vmcnt(8)
	s_barrier
	s_setprio 1
	v_mfma_f32_16x16x32_bf16 v[88:91], v[8:11], v[24:27], v[88:91]
	v_mfma_f32_16x16x32_bf16 v[84:87], v[16:19], v[24:27], v[84:87]
	s_setprio 0
	s_cmp_eq_u32 s77, 12
	s_cbranch_scc1 .Lq5_o_n0
	s_mov_b32 m0, s51
	v_lshl_add_u64 v[2:3], s[56:57], 0, v[198:199]
	s_add_u32 s78, s56, 0x80000
	global_load_lds_dwordx4 v[2:3], off
	v_lshl_add_u64 v[204:205], s[56:57], 0, v[196:197]
	s_mov_b32 m0, s60
	s_addc_u32 s79, s57, 0
	global_load_lds_dwordx4 v[204:205], off
	v_lshl_add_u64 v[206:207], s[78:79], 0, v[198:199]
	s_mov_b32 m0, s66
	v_lshl_add_u64 v[208:209], s[58:59], 0, v[196:197]
	v_lshl_add_u64 v[206:207], s[78:79], 0, v[196:197]
	s_mov_b32 m0, s67
	s_and_b64 vcc, exec, s[2:3]
	v_lshl_add_u64 v[206:207], s[58:59], 0, v[198:199]
	s_mov_b32 m0, s62
	s_nop 0
	global_load_lds_dwordx4 v[206:207], off
	s_mov_b32 m0, s63
	s_nop 0
	global_load_lds_dwordx4 v[208:209], off
.Lq5_o_n0:
	s_barrier
	v_add_u32_e32 v1, 0x1c000, v213
	ds_read_b128 v[4:7], v1
	ds_read_b128 v[8:11], v1 offset:1024
	ds_read_b128 v[12:15], v1 offset:2048
	ds_read_b128 v[16:19], v1 offset:3072
	v_add_u32_e32 v1, 0x1c000, v213
	s_add_u32 s58, s58, 0x80000
	s_addc_u32 s59, s59, 0
	s_mov_b32 m0, s62
	v_lshl_add_u64 v[218:219], s[58:59], 0, v[198:199]
	ds_read_b128 v[44:47], v216 offset:49152
	ds_read_b128 v[48:51], v216 offset:50176
	ds_read_b128 v[36:39], v216 offset:51200
	ds_read_b128 v[40:43], v216 offset:52224
	ds_read_b128 v[28:31], v216 offset:53248
	ds_read_b128 v[32:35], v216 offset:54272
	ds_read_b128 v[20:23], v216 offset:55296
	ds_read_b128 v[24:27], v216 offset:56320
	v_lshl_add_u64 v[218:219], s[58:59], 0, v[196:197]
	s_mov_b32 m0, s63
	s_nop 0
	s_setprio 1
	v_mfma_f32_16x16x32_bf16 v[128:131], v[148:151], v[188:191], v[128:131]
	v_mfma_f32_16x16x32_bf16 v[124:127], v[156:159], v[188:191], v[124:127]
	v_mfma_f32_16x16x32_bf16 v[120:123], v[148:151], v[180:183], v[120:123]
	v_mfma_f32_16x16x32_bf16 v[116:119], v[156:159], v[180:183], v[116:119]
	v_mfma_f32_16x16x32_bf16 v[104:107], v[148:151], v[172:175], v[104:107]
	v_mfma_f32_16x16x32_bf16 v[100:103], v[156:159], v[172:175], v[100:103]
	s_setprio 0
	s_barrier
	s_and_b64 vcc, exec, s[2:3]
	s_setprio 1
	v_mfma_f32_16x16x32_bf16 v[88:91], v[148:151], v[164:167], v[88:91]
	v_mfma_f32_16x16x32_bf16 v[84:87], v[156:159], v[164:167], v[84:87]
	v_mfma_f32_16x16x32_bf16 v[128:131], v[152:155], v[192:195], v[128:131]
	v_mfma_f32_16x16x32_bf16 v[124:127], v[160:163], v[192:195], v[124:127]
	v_mfma_f32_16x16x32_bf16 v[120:123], v[152:155], v[184:187], v[120:123]
	s_setprio 0
	s_waitcnt lgkmcnt(0)
	s_barrier
	s_setprio 1
	v_mfma_f32_16x16x32_bf16 v[116:119], v[160:163], v[184:187], v[116:119]
	v_mfma_f32_16x16x32_bf16 v[104:107], v[152:155], v[176:179], v[104:107]
	v_mfma_f32_16x16x32_bf16 v[100:103], v[160:163], v[176:179], v[100:103]
	s_setprio 0
	s_waitcnt vmcnt(8)
	s_cmp_eq_u32 s77, 12
	s_cbranch_scc0 .Lq5_o_w
	s_waitcnt vmcnt(4)
.Lq5_o_w:
	s_barrier
	s_setprio 1
	v_mfma_f32_16x16x32_bf16 v[88:91], v[152:155], v[168:171], v[88:91]
	v_mfma_f32_16x16x32_bf16 v[84:87], v[160:163], v[168:171], v[84:87]
	s_setprio 0
	s_cmp_eq_u32 s77, 12
	s_cbranch_scc1 .Lq5_o_n1
	s_mov_b32 m0, s70
	v_lshl_add_u64 v[2:3], v[2:3], 0, s[16:17]
	s_add_u32 s56, s56, 0x80080
	global_load_lds_dwordx4 v[2:3], off
	v_lshl_add_u64 v[2:3], v[204:205], 0, s[16:17]
	s_mov_b32 m0, s71
	s_addc_u32 s57, s57, 0
	global_load_lds_dwordx4 v[2:3], off
	v_lshl_add_u64 v[2:3], s[56:57], 0, v[198:199]
	s_add_i32 m0, s48, 0x20000
	s_and_b64 vcc, exec, s[2:3]
	v_lshl_add_u64 v[2:3], s[56:57], 0, v[196:197]
	s_add_i32 m0, s48, 0x22000
	s_nop 0
	v_lshl_add_u64 v[2:3], v[206:207], 0, s[16:17]
	s_add_i32 m0, s48, 0xc000
	s_nop 0
	global_load_lds_dwordx4 v[2:3], off
	v_lshl_add_u64 v[2:3], v[208:209], 0, s[16:17]
	s_add_i32 m0, s48, 0xe000
	s_nop 0
	global_load_lds_dwordx4 v[2:3], off

.LBB0_1281:
	s_cmp_lt_i32 s79, 1
	s_cselect_b64 s[34:35], -1, 0
	s_add_u32 s38, s38, 0x80080
	s_addc_u32 s39, s39, 0
	v_mov_b32_e32 v2, v0
	v_mov_b32_e32 v3, v0
	s_add_u32 s16, s4, 0x100
	v_mov_b32_e32 v1, v0
	v_mov_b32_e32 v112, 0
	v_mov_b64_e32 v[6:7], v[2:3]
	v_mov_b64_e32 v[10:11], v[2:3]
	v_mov_b64_e32 v[22:23], v[2:3]
	v_mov_b64_e32 v[26:27], v[2:3]
	v_mov_b64_e32 v[38:39], v[2:3]
	v_mov_b64_e32 v[42:43], v[2:3]
	v_mov_b64_e32 v[54:55], v[2:3]
	v_mov_b64_e32 v[58:59], v[2:3]
	v_mov_b64_e32 v[14:15], v[2:3]
	v_mov_b64_e32 v[18:19], v[2:3]
	v_mov_b64_e32 v[30:31], v[2:3]
	v_mov_b64_e32 v[34:35], v[2:3]
	v_mov_b64_e32 v[46:47], v[2:3]
	v_mov_b64_e32 v[50:51], v[2:3]
	v_mov_b64_e32 v[62:63], v[2:3]
	v_mov_b64_e32 v[66:67], v[2:3]
	v_mov_b64_e32 v[90:91], v[2:3]
	v_mov_b64_e32 v[106:107], v[2:3]
	v_mov_b64_e32 v[110:111], v[2:3]
	v_mov_b64_e32 v[118:119], v[2:3]
	v_mov_b64_e32 v[126:127], v[2:3]
	v_mov_b64_e32 v[130:131], v[2:3]
	v_mov_b64_e32 v[142:143], v[2:3]
	v_mov_b64_e32 v[146:147], v[2:3]
	s_addc_u32 s27, s5, 0
	s_mov_b32 s84, -2
	v_cndmask_b32_e64 v251, 0, 1, s[34:35]
	v_mov_b64_e32 v[4:5], v[0:1]
	v_mov_b64_e32 v[8:9], v[0:1]
	v_mov_b64_e32 v[20:21], v[0:1]
	v_mov_b64_e32 v[24:25], v[0:1]
	v_mov_b64_e32 v[36:37], v[0:1]
	v_mov_b64_e32 v[40:41], v[0:1]
	v_mov_b64_e32 v[52:53], v[0:1]
	v_mov_b64_e32 v[56:57], v[0:1]
	v_mov_b64_e32 v[12:13], v[0:1]
	v_mov_b64_e32 v[16:17], v[0:1]
	v_mov_b64_e32 v[28:29], v[0:1]
	v_mov_b64_e32 v[32:33], v[0:1]
	v_mov_b64_e32 v[44:45], v[0:1]
	v_mov_b64_e32 v[48:49], v[0:1]
	v_mov_b64_e32 v[60:61], v[0:1]
	v_mov_b64_e32 v[64:65], v[0:1]
	v_mov_b64_e32 v[88:89], v[0:1]
	v_mov_b64_e32 v[104:105], v[0:1]
	v_mov_b64_e32 v[108:109], v[0:1]
	v_mov_b64_e32 v[116:117], v[0:1]
	v_mov_b64_e32 v[124:125], v[0:1]
	v_mov_b64_e32 v[128:129], v[0:1]
	v_mov_b64_e32 v[140:141], v[0:1]
	v_mov_b64_e32 v[144:145], v[0:1]
	v_mov_b32_e32 v113, v112
	v_mov_b32_e32 v114, v112
	v_mov_b32_e32 v115, v112
	v_mov_b32_e32 v120, v112
	v_mov_b32_e32 v121, v112
	v_mov_b32_e32 v122, v112
	v_mov_b32_e32 v123, v112
	v_mov_b32_e32 v132, v112
	v_mov_b32_e32 v133, v112
	v_mov_b32_e32 v134, v112
	v_mov_b32_e32 v135, v112
	v_mov_b32_e32 v136, v112
	v_mov_b32_e32 v137, v112
	v_mov_b32_e32 v138, v112
	v_mov_b32_e32 v139, v112
	v_mov_b32_e32 v148, v112
	v_mov_b32_e32 v149, v112
	v_mov_b32_e32 v150, v112
	v_mov_b32_e32 v151, v112
	v_mov_b32_e32 v152, v112
	v_mov_b32_e32 v153, v112
	v_mov_b32_e32 v154, v112
	v_mov_b32_e32 v155, v112
	v_mov_b32_e32 v156, v112
	v_mov_b32_e32 v157, v112
	v_mov_b32_e32 v158, v112
	v_mov_b32_e32 v159, v112
	v_mov_b32_e32 v160, v112
	v_mov_b32_e32 v161, v112
	v_mov_b32_e32 v162, v112
	v_mov_b32_e32 v163, v112
	s_branch .LBB0_1283
	s_nop 0
	s_nop 0
	s_nop 0
.LBB0_1282:
	s_barrier
	s_add_i32 s84, s84, 2
	s_add_u32 s38, s38, 0x100
	s_addc_u32 s39, s39, 0
	s_add_u32 s16, s16, 0x100
	s_addc_u32 s27, s27, 0
	s_cmp_gt_u32 s84, 29
	s_cbranch_scc1 .LBB0_1291

.Lq6_top:
	ds_read_b128 v[180:183], v247
	ds_read_b128 v[184:187], v247 offset:1024
	ds_read_b128 v[188:191], v247 offset:2048
	ds_read_b128 v[192:195], v247 offset:3072
	v_lshl_add_u64 v[2:3], s[38:39], 0, v[232:233]
	s_add_i32 m0, s44, 0xc000
	ds_read_b128 v[220:223], v249
	ds_read_b128 v[224:227], v249 offset:1024
	ds_read_b128 v[212:215], v249 offset:2048
	ds_read_b128 v[216:219], v249 offset:3072
	ds_read_b128 v[204:207], v249 offset:4096
	ds_read_b128 v[208:211], v249 offset:5120
	ds_read_b128 v[196:199], v249 offset:6144
	ds_read_b128 v[200:203], v249 offset:7168
	v_lshl_add_u64 v[2:3], s[38:39], 0, v[234:235]
	s_add_i32 m0, s44, 0xe000
	s_nop 0
	s_setprio 1
	v_mfma_f32_16x16x32_bf16 v[68:71], v[4:7], v[44:47], v[160:163]
	v_mfma_f32_16x16x32_bf16 v[72:75], v[12:15], v[44:47], v[156:159]
	v_mfma_f32_16x16x32_bf16 v[76:79], v[4:7], v[36:39], v[152:155]
	v_mfma_f32_16x16x32_bf16 v[80:83], v[12:15], v[36:39], v[148:151]
	v_mfma_f32_16x16x32_bf16 v[84:87], v[4:7], v[28:31], v[136:139]
	v_mfma_f32_16x16x32_bf16 v[92:95], v[12:15], v[28:31], v[132:135]
	s_setprio 0
	s_barrier
	v_cmp_ne_u32_e64 s[4:5], 1, v251
	s_andn2_b64 vcc, exec, s[34:35]
	s_add_u32 s40, s38, 0xfff80080
	s_addc_u32 s41, s39, -1
	s_cmp_eq_u32 s84, 26
	s_cselect_b32 s47, s29, s41
	s_cselect_b32 s46, s28, s40
	s_cselect_b32 s41, s37, s27
	s_cselect_b32 s40, s36, s16
	s_setprio 1
	v_mfma_f32_16x16x32_bf16 v[96:99], v[4:7], v[20:23], v[120:123]
	v_mfma_f32_16x16x32_bf16 v[100:103], v[12:15], v[20:23], v[112:115]
	v_mfma_f32_16x16x32_bf16 v[68:71], v[8:11], v[48:51], v[68:71]
	v_mfma_f32_16x16x32_bf16 v[72:75], v[16:19], v[48:51], v[72:75]
	v_mfma_f32_16x16x32_bf16 v[76:79], v[8:11], v[40:43], v[76:79]
	s_setprio 0
	s_waitcnt lgkmcnt(0)
	s_barrier
	s_setprio 1
	v_mfma_f32_16x16x32_bf16 v[80:83], v[16:19], v[40:43], v[80:83]
	v_mfma_f32_16x16x32_bf16 v[84:87], v[8:11], v[32:35], v[84:87]
	v_mfma_f32_16x16x32_bf16 v[92:95], v[16:19], v[32:35], v[92:95]
	s_setprio 0
	s_waitcnt vmcnt(8)
	s_barrier
	s_setprio 1
	v_mfma_f32_16x16x32_bf16 v[96:99], v[8:11], v[24:27], v[96:99]
	v_mfma_f32_16x16x32_bf16 v[100:103], v[16:19], v[24:27], v[100:103]
	s_setprio 0
	s_mov_b32 m0, s45
	v_lshl_add_u64 v[2:3], s[40:41], 0, v[230:231]
	s_add_u32 s86, s40, 0x80000
	global_load_lds_dwordx4 v[2:3], off
	v_lshl_add_u64 v[236:237], s[40:41], 0, v[228:229]
	s_mov_b32 m0, s48
	s_addc_u32 s87, s41, 0
	global_load_lds_dwordx4 v[236:237], off
	v_lshl_add_u64 v[54:55], s[86:87], 0, v[230:231]
	s_mov_b32 m0, s49
	v_lshl_add_u64 v[238:239], s[46:47], 0, v[230:231]
	v_lshl_add_u64 v[54:55], s[86:87], 0, v[228:229]
	s_mov_b32 m0, s50
	v_lshl_add_u64 v[240:241], s[46:47], 0, v[228:229]
	s_mov_b32 m0, s44
	s_and_b64 vcc, exec, s[4:5]
	global_load_lds_dwordx4 v[238:239], off
	s_mov_b32 m0, s51
	s_nop 0
	global_load_lds_dwordx4 v[240:241], off
	s_barrier
	v_add_u32_e32 v1, 0x18000, v246
	ds_read_b128 v[4:7], v1
	ds_read_b128 v[8:11], v1 offset:1024
	ds_read_b128 v[12:15], v1 offset:2048
	ds_read_b128 v[16:19], v1 offset:3072
	v_add_u32_e32 v1, 0x1c000, v246
	s_add_u32 s46, s46, 0x80000
	s_addc_u32 s47, s47, 0
	s_mov_b32 m0, s56
	v_lshl_add_u64 v[112:113], s[46:47], 0, v[230:231]
	ds_read_b128 v[44:47], v249 offset:32768
	ds_read_b128 v[48:51], v249 offset:33792
	ds_read_b128 v[36:39], v249 offset:34816
	ds_read_b128 v[40:43], v249 offset:35840
	ds_read_b128 v[28:31], v249 offset:36864
	ds_read_b128 v[32:35], v249 offset:37888
	ds_read_b128 v[20:23], v249 offset:38912
	ds_read_b128 v[24:27], v249 offset:39936
	v_lshl_add_u64 v[112:113], s[46:47], 0, v[228:229]
	s_mov_b32 m0, s57
	s_nop 0
	s_setprio 1
	v_mfma_f32_16x16x32_bf16 v[68:71], v[180:183], v[220:223], v[68:71]
	v_mfma_f32_16x16x32_bf16 v[160:163], v[184:187], v[224:227], v[68:71]
	v_mfma_f32_16x16x32_bf16 v[68:71], v[188:191], v[220:223], v[72:75]
	v_mfma_f32_16x16x32_bf16 v[156:159], v[192:195], v[224:227], v[68:71]
	v_mfma_f32_16x16x32_bf16 v[68:71], v[180:183], v[212:215], v[76:79]
	v_mfma_f32_16x16x32_bf16 v[152:155], v[184:187], v[216:219], v[68:71]
	s_setprio 0
	s_barrier
	s_and_b64 vcc, exec, s[4:5]
	s_setprio 1
	v_mfma_f32_16x16x32_bf16 v[68:71], v[188:191], v[212:215], v[80:83]
	v_mfma_f32_16x16x32_bf16 v[148:151], v[192:195], v[216:219], v[68:71]
	v_mfma_f32_16x16x32_bf16 v[68:71], v[180:183], v[204:207], v[84:87]
	v_mfma_f32_16x16x32_bf16 v[136:139], v[184:187], v[208:211], v[68:71]
	v_mfma_f32_16x16x32_bf16 v[68:71], v[188:191], v[204:207], v[92:95]
	s_setprio 0
	s_waitcnt lgkmcnt(0)
	s_barrier
	s_setprio 1
	v_mfma_f32_16x16x32_bf16 v[132:135], v[192:195], v[208:211], v[68:71]
	v_mfma_f32_16x16x32_bf16 v[68:71], v[180:183], v[196:199], v[96:99]
	v_mfma_f32_16x16x32_bf16 v[120:123], v[184:187], v[200:203], v[68:71]
	s_setprio 0
	s_waitcnt vmcnt(8)
	s_barrier
	s_setprio 1
	v_mfma_f32_16x16x32_bf16 v[68:71], v[188:191], v[196:199], v[100:103]
	v_mfma_f32_16x16x32_bf16 v[112:115], v[192:195], v[200:203], v[68:71]
	s_setprio 0
	s_mov_b32 m0, s61
	v_lshl_add_u64 v[2:3], v[2:3], 0, s[14:15]
	s_add_u32 s40, s40, 0x80080
	global_load_lds_dwordx4 v[2:3], off
	v_lshl_add_u64 v[2:3], v[236:237], 0, s[14:15]
	s_mov_b32 m0, s62
	s_addc_u32 s41, s41, 0
	global_load_lds_dwordx4 v[2:3], off
	v_lshl_add_u64 v[2:3], s[40:41], 0, v[230:231]
	s_mov_b32 m0, s65
	s_and_b64 vcc, exec, s[4:5]
	v_lshl_add_u64 v[2:3], s[40:41], 0, v[228:229]
	s_mov_b32 m0, s66
	s_nop 0
	v_lshl_add_u64 v[2:3], v[238:239], 0, s[14:15]
	s_mov_b32 m0, s63
	s_nop 0
	global_load_lds_dwordx4 v[2:3], off
	v_lshl_add_u64 v[2:3], v[240:241], 0, s[14:15]
	s_mov_b32 m0, s64
	s_nop 0
	global_load_lds_dwordx4 v[2:3], off
	s_barrier
	s_add_i32 s84, s84, 2
	s_add_u32 s38, s38, 0x100
	s_addc_u32 s39, s39, 0
	s_add_u32 s16, s16, 0x100
	s_addc_u32 s27, s27, 0
	s_cmp_gt_u32 s84, 29
	ds_read_b128 v[180:183], v248
	ds_read_b128 v[184:187], v248 offset:1024
	ds_read_b128 v[188:191], v248 offset:2048
	ds_read_b128 v[192:195], v248 offset:3072
	v_lshl_add_u64 v[2:3], s[38:39], 0, v[232:233]
	s_add_i32 m0, s44, 0xc000
	ds_read_b128 v[220:223], v249 offset:16384
	ds_read_b128 v[224:227], v249 offset:17408
	ds_read_b128 v[212:215], v249 offset:18432
	ds_read_b128 v[216:219], v249 offset:19456
	ds_read_b128 v[204:207], v249 offset:20480
	ds_read_b128 v[208:211], v249 offset:21504
	ds_read_b128 v[196:199], v249 offset:22528
	ds_read_b128 v[200:203], v249 offset:23552
	v_lshl_add_u64 v[2:3], s[38:39], 0, v[234:235]
	s_add_i32 m0, s44, 0xe000
	s_nop 0
	s_setprio 1
	v_mfma_f32_16x16x32_bf16 v[68:71], v[4:7], v[44:47], v[160:163]
	v_mfma_f32_16x16x32_bf16 v[72:75], v[12:15], v[44:47], v[156:159]
	v_mfma_f32_16x16x32_bf16 v[76:79], v[4:7], v[36:39], v[152:155]
	v_mfma_f32_16x16x32_bf16 v[80:83], v[12:15], v[36:39], v[148:151]
	v_mfma_f32_16x16x32_bf16 v[84:87], v[4:7], v[28:31], v[136:139]
	v_mfma_f32_16x16x32_bf16 v[92:95], v[12:15], v[28:31], v[132:135]
	s_setprio 0
	s_barrier
	v_cmp_ne_u32_e64 s[4:5], 1, v251
	s_andn2_b64 vcc, exec, s[34:35]
	s_add_u32 s40, s38, 0xfff80080
	s_addc_u32 s41, s39, -1
	s_cmp_eq_u32 s84, 28
	s_cselect_b32 s47, s29, s41
	s_cselect_b32 s46, s28, s40
	s_cselect_b32 s41, s37, s27
	s_cselect_b32 s40, s36, s16
	s_setprio 1
	v_mfma_f32_16x16x32_bf16 v[96:99], v[4:7], v[20:23], v[120:123]
	v_mfma_f32_16x16x32_bf16 v[100:103], v[12:15], v[20:23], v[112:115]
	v_mfma_f32_16x16x32_bf16 v[68:71], v[8:11], v[48:51], v[68:71]
	v_mfma_f32_16x16x32_bf16 v[72:75], v[16:19], v[48:51], v[72:75]
	v_mfma_f32_16x16x32_bf16 v[76:79], v[8:11], v[40:43], v[76:79]
	s_setprio 0
	s_waitcnt lgkmcnt(0)
	s_barrier
	s_setprio 1
	v_mfma_f32_16x16x32_bf16 v[80:83], v[16:19], v[40:43], v[80:83]
	v_mfma_f32_16x16x32_bf16 v[84:87], v[8:11], v[32:35], v[84:87]
	v_mfma_f32_16x16x32_bf16 v[92:95], v[16:19], v[32:35], v[92:95]
	s_setprio 0
	s_waitcnt vmcnt(8)
	s_barrier
	s_setprio 1
	v_mfma_f32_16x16x32_bf16 v[96:99], v[8:11], v[24:27], v[96:99]
	v_mfma_f32_16x16x32_bf16 v[100:103], v[16:19], v[24:27], v[100:103]
	s_setprio 0
	s_cmp_eq_u32 s84, 28
	s_cbranch_scc1 .Lq6_o_n0
	s_mov_b32 m0, s49
	v_lshl_add_u64 v[2:3], s[40:41], 0, v[230:231]
	s_add_u32 s86, s40, 0x80000
	global_load_lds_dwordx4 v[2:3], off
	v_lshl_add_u64 v[236:237], s[40:41], 0, v[228:229]
	s_mov_b32 m0, s50
	s_addc_u32 s87, s41, 0
	global_load_lds_dwordx4 v[236:237], off
	v_lshl_add_u64 v[54:55], s[86:87], 0, v[230:231]
	s_mov_b32 m0, s61
	v_lshl_add_u64 v[238:239], s[46:47], 0, v[230:231]
	v_lshl_add_u64 v[54:55], s[86:87], 0, v[228:229]
	s_mov_b32 m0, s62
	v_lshl_add_u64 v[240:241], s[46:47], 0, v[228:229]
	s_mov_b32 m0, s56
	s_and_b64 vcc, exec, s[4:5]
	global_load_lds_dwordx4 v[238:239], off
	s_mov_b32 m0, s57
	s_nop 0
	global_load_lds_dwordx4 v[240:241], off
.Lq6_o_n0:
	s_barrier
	v_add_u32_e32 v1, 0x1c000, v246
	ds_read_b128 v[4:7], v1
	ds_read_b128 v[8:11], v1 offset:1024
	ds_read_b128 v[12:15], v1 offset:2048
	ds_read_b128 v[16:19], v1 offset:3072
	v_add_u32_e32 v1, 0x1c000, v246
	s_add_u32 s46, s46, 0x80000
	s_addc_u32 s47, s47, 0
	s_mov_b32 m0, s56
	v_lshl_add_u64 v[112:113], s[46:47], 0, v[230:231]
	ds_read_b128 v[44:47], v249 offset:49152
	ds_read_b128 v[48:51], v249 offset:50176
	ds_read_b128 v[36:39], v249 offset:51200
	ds_read_b128 v[40:43], v249 offset:52224
	ds_read_b128 v[28:31], v249 offset:53248
	ds_read_b128 v[32:35], v249 offset:54272
	ds_read_b128 v[20:23], v249 offset:55296
	ds_read_b128 v[24:27], v249 offset:56320
	v_lshl_add_u64 v[112:113], s[46:47], 0, v[228:229]
	s_mov_b32 m0, s57
	s_nop 0
	s_setprio 1
	v_mfma_f32_16x16x32_bf16 v[68:71], v[180:183], v[220:223], v[68:71]
	v_mfma_f32_16x16x32_bf16 v[160:163], v[184:187], v[224:227], v[68:71]
	v_mfma_f32_16x16x32_bf16 v[68:71], v[188:191], v[220:223], v[72:75]
	v_mfma_f32_16x16x32_bf16 v[156:159], v[192:195], v[224:227], v[68:71]
	v_mfma_f32_16x16x32_bf16 v[68:71], v[180:183], v[212:215], v[76:79]
	v_mfma_f32_16x16x32_bf16 v[152:155], v[184:187], v[216:219], v[68:71]
	s_setprio 0
	s_barrier
	s_and_b64 vcc, exec, s[4:5]
	s_setprio 1
	v_mfma_f32_16x16x32_bf16 v[68:71], v[188:191], v[212:215], v[80:83]
	v_mfma_f32_16x16x32_bf16 v[148:151], v[192:195], v[216:219], v[68:71]
	v_mfma_f32_16x16x32_bf16 v[68:71], v[180:183], v[204:207], v[84:87]
	v_mfma_f32_16x16x32_bf16 v[136:139], v[184:187], v[208:211], v[68:71]
	v_mfma_f32_16x16x32_bf16 v[68:71], v[188:191], v[204:207], v[92:95]
	s_setprio 0
	s_waitcnt lgkmcnt(0)
	s_barrier
	s_setprio 1
	v_mfma_f32_16x16x32_bf16 v[132:135], v[192:195], v[208:211], v[68:71]
	v_mfma_f32_16x16x32_bf16 v[68:71], v[180:183], v[196:199], v[96:99]
	v_mfma_f32_16x16x32_bf16 v[120:123], v[184:187], v[200:203], v[68:71]
	s_setprio 0
	s_waitcnt vmcnt(8)
	s_cmp_eq_u32 s84, 28
	s_cbranch_scc0 .Lq6_o_w
	s_waitcnt vmcnt(4)
.Lq6_o_w:
	s_barrier
	s_setprio 1
	v_mfma_f32_16x16x32_bf16 v[68:71], v[188:191], v[196:199], v[100:103]
	v_mfma_f32_16x16x32_bf16 v[112:115], v[192:195], v[200:203], v[68:71]
	s_setprio 0
	s_cmp_eq_u32 s84, 28
	s_cbranch_scc1 .Lq6_o_n1
	s_mov_b32 m0, s65
	v_lshl_add_u64 v[2:3], v[2:3], 0, s[14:15]
	s_add_u32 s40, s40, 0x80080
	global_load_lds_dwordx4 v[2:3], off
	v_lshl_add_u64 v[2:3], v[236:237], 0, s[14:15]
	s_mov_b32 m0, s66
	s_addc_u32 s41, s41, 0
	global_load_lds_dwordx4 v[2:3], off
	v_lshl_add_u64 v[2:3], s[40:41], 0, v[230:231]
	s_add_i32 m0, s44, 0x20000
	s_and_b64 vcc, exec, s[4:5]
	v_lshl_add_u64 v[2:3], s[40:41], 0, v[228:229]
	s_add_i32 m0, s44, 0x22000
	s_nop 0
	v_lshl_add_u64 v[2:3], v[238:239], 0, s[14:15]
	s_add_i32 m0, s44, 0xc000
	s_nop 0
	global_load_lds_dwordx4 v[2:3], off
	v_lshl_add_u64 v[2:3], v[240:241], 0, s[14:15]
	s_add_i32 m0, s44, 0xe000
	s_nop 0
	global_load_lds_dwordx4 v[2:3], off
